# speedup vs baseline: 1.0164x; 1.0006x over previous
; __device__ __forceinline__ int tid_fresh() { int t = (int)threadIdx.x; asm volatile("" : "+v"(t)); return t; }
; __device__ __forceinline__ void conv_phase(const bf16_t* Z, bf16_t* UA, const float* cw, const float* cb, int nrows, int rowoff) {
;     const int gtid = blockIdx.x * 512 + tid_fresh(), NT = gridDim.x * 512; const int total = (nrows / 16) * 352;
;     for (int idx = gtid; idx < total; idx += NT) {
;         const int cgp = idx % 352, rb = idx / 352, c0 = cgp * 8, r0 = rb * 16, grow0 = rowoff + r0;
;         const int seg = grow0 < MLAT ? SEQ : CTXL; const bool has_left = (grow0 & (seg - 1)) != 0, has_right = ((grow0 + 16) & (seg - 1)) != 0;
;         float wa[3][8], wg[3][8], ba[8], bg[8];
; #pragma unroll
;         for (int j = 0; j < 3; ++j)
; #pragma unroll
;             for (int h = 0; h < 2; ++h) { const f32x4 x = *(const f32x4*)(cw + j * FFN2 + c0 + 4 * h), y = *(const f32x4*)(cw + j * FFN2 + FFN + c0 + 4 * h);
; #pragma unroll
;                 for (int e = 0; e < 4; ++e) { wa[j][4 * h + e] = x[e]; wg[j][4 * h + e] = y[e]; } }
; #pragma unroll
;         for (int h = 0; h < 2; ++h) { const f32x4 x = *(const f32x4*)(cb + c0 + 4 * h), y = *(const f32x4*)(cb + FFN + c0 + 4 * h);
; #pragma unroll
;             for (int e = 0; e < 4; ++e) { ba[4 * h + e] = x[e]; bg[4 * h + e] = y[e]; } }
;         const bf16_t* zp = Z + (size_t)r0 * FFN2 + c0; const u32x4 zero = (u32x4){0u, 0u, 0u, 0u};
;         u32x4 pa = zero, pg = zero; if (has_left) { pa = *(const u32x4*)(zp - FFN2); pg = *(const u32x4*)(zp - FFN2 + FFN); }
;         u32x4 ca = *(const u32x4*)(zp), cgv = *(const u32x4*)(zp + FFN);
.LBB0_459:
	s_or_b64 exec, exec, s[2:3]
	v_mov_b32_e32 v1, v204
	v_readlane_b32 s2, v255, 17
	s_lshr_b32 s12, s45, 4
	s_waitcnt lgkmcnt(0)
	s_barrier
	s_mulk_i32 s12, 0x160
	s_xor_b64 s[88:89], s[40:41], -1
	s_lshr_b32 s13, s45, 4
	v_readlane_b32 s2, v254, 21
	v_readlane_b32 s3, v254, 22
	v_readlane_b32 s98, v255, 17
	s_load_dwordx2 s[38:39], s[2:3], 0x98
	s_load_dwordx2 s[40:41], s[2:3], 0xa0
	s_add_u32 s36, s54, 0x23a00000
	s_addc_u32 s37, s55, 0
	v_mov_b32_e32 v180, 0xbfb8aa3b
	v_mov_b32_e32 v181, 0xbfb8aa3b
	v_mov_b32_e32 v144, 1.0
	v_mov_b32_e32 v145, 1.0
	s_lshr_b32 s99, s98, 9
	v_lshrrev_b32_e32 v1, 6, v204
	v_lshl_add_u32 v1, v1, 8, s99
	v_and_b32_e32 v9, 63, v204
	v_lshl_or_b32 v1, v1, 6, v9
	s_mov_b32 s99, 0x2e8ba2e9
	v_mul_hi_u32 v2, v1, s99
	v_lshrrev_b32_e32 v2, 6, v2
	v_mul_u32_u24_e32 v3, 0x160, v2
	v_sub_u32_e32 v3, v1, v3
	v_lshlrev_b32_e32 v4, 5, v3
	v_mul_u32_u24_e32 v5, 180224, v2
	v_lshl_add_u32 v5, v3, 4, v5
	v_mul_u32_u24_e32 v6, 90112, v2
	v_lshl_add_u32 v6, v3, 4, v6
	s_lshr_b32 s99, s43, 4
	v_add_u32_e32 v7, s99, v2
	s_waitcnt lgkmcnt(0)
	s_sub_u32 s2, s64, 0x4000
	s_subb_u32 s3, s65, 0
	s_mov_b32 s98, 0
	s_mov_b32 s99, 0xffff0000
	global_load_dwordx4 v[152:155], v4, s[38:39]
	global_load_dwordx4 v[156:159], v4, s[38:39] offset:16
	v_add_u32_e32 v10, 11264, v4
	global_load_dwordx4 v[212:215], v10, s[38:39]
	global_load_dwordx4 v[216:219], v10, s[38:39] offset:16
	v_add_u32_e32 v11, 22528, v4
	global_load_dwordx4 v[160:163], v11, s[38:39]
	global_load_dwordx4 v[164:167], v11, s[38:39] offset:16
	v_add_u32_e32 v10, 33792, v4
	global_load_dwordx4 v[220:223], v10, s[38:39]
	global_load_dwordx4 v[224:227], v10, s[38:39] offset:16
	v_add_u32_e32 v11, 45056, v4
	global_load_dwordx4 v[168:171], v11, s[38:39]
	global_load_dwordx4 v[172:175], v11, s[38:39] offset:16
	v_add_u32_e32 v10, 56320, v4
	global_load_dwordx4 v[228:231], v10, s[38:39]
	global_load_dwordx4 v[232:235], v10, s[38:39] offset:16
	global_load_dwordx4 v[236:239], v4, s[40:41]
	global_load_dwordx4 v[240:243], v4, s[40:41] offset:16
	v_add_u32_e32 v11, 11264, v4
	global_load_dwordx4 v[244:247], v11, s[40:41]
	global_load_dwordx4 v[248:251], v11, s[40:41] offset:16
	v_add_u32_e32 v10, 7936, v5
	global_load_dwordx4 v[64:67], v10, s[2:3] offset:-2816 nt
	global_load_dwordx4 v[68:71], v10, s[2:3] offset:2816 nt
	global_load_dword v252, v4, s[40:41]
	v_add_u32_e32 v11, 19200, v5
	global_load_dwordx4 v[72:75], v11, s[2:3] offset:-2816 nt
	global_load_dwordx4 v[76:79], v11, s[2:3] offset:2816 nt
	global_load_dword v252, v4, s[40:41]
	v_add_u32_e32 v10, 30464, v5
	global_load_dwordx4 v[80:83], v10, s[2:3] offset:-2816 nt
	global_load_dwordx4 v[84:87], v10, s[2:3] offset:2816 nt
	global_load_dword v252, v4, s[40:41]
	v_add_u32_e32 v11, 41728, v5
	global_load_dwordx4 v[88:91], v11, s[2:3] offset:-2816 nt
	global_load_dwordx4 v[92:95], v11, s[2:3] offset:2816 nt
	global_load_dword v252, v4, s[40:41]
	v_add_u32_e32 v10, 52992, v5
	global_load_dwordx4 v[96:99], v10, s[2:3] offset:-2816 nt
	global_load_dwordx4 v[100:103], v10, s[2:3] offset:2816 nt
	global_load_dword v252, v4, s[40:41]
	v_add_u32_e32 v11, 64256, v5
	global_load_dwordx4 v[104:107], v11, s[2:3] offset:-2816 nt
	global_load_dwordx4 v[108:111], v11, s[2:3] offset:2816 nt
	global_load_dword v252, v4, s[40:41]
	v_add_u32_e32 v10, 75520, v5
	global_load_dwordx4 v[112:115], v10, s[2:3] offset:-2816 nt
	global_load_dwordx4 v[116:119], v10, s[2:3] offset:2816 nt
	global_load_dword v252, v4, s[40:41]
	v_add_u32_e32 v11, 86784, v5
	global_load_dwordx4 v[120:123], v11, s[2:3] offset:-2816 nt
	global_load_dwordx4 v[124:127], v11, s[2:3] offset:2816 nt
	global_load_dword v252, v4, s[40:41]
	v_add_u32_e32 v10, 98048, v5
	global_load_dwordx4 v[128:131], v10, s[2:3] offset:-2816 nt
	global_load_dwordx4 v[132:135], v10, s[2:3] offset:2816 nt
	global_load_dword v252, v4, s[40:41]

; __device__ __forceinline__ int tid_fresh() { int t = (int)threadIdx.x; asm volatile("" : "+v"(t)); return t; }
; __device__ __forceinline__ void conv_phase(const bf16_t* Z, bf16_t* UA, const float* cw, const float* cb, int nrows, int rowoff) {
;     const int gtid = blockIdx.x * 512 + tid_fresh(), NT = gridDim.x * 512; const int total = (nrows / 16) * 352;
;     for (int idx = gtid; idx < total; idx += NT) {
;         const int cgp = idx % 352, rb = idx / 352, c0 = cgp * 8, r0 = rb * 16, grow0 = rowoff + r0;
;         const int seg = grow0 < MLAT ? SEQ : CTXL; const bool has_left = (grow0 & (seg - 1)) != 0, has_right = ((grow0 + 16) & (seg - 1)) != 0;
;         float wa[3][8], wg[3][8], ba[8], bg[8];
; #pragma unroll
;         for (int j = 0; j < 3; ++j)
; #pragma unroll
;             for (int h = 0; h < 2; ++h) { const f32x4 x = *(const f32x4*)(cw + j * FFN2 + c0 + 4 * h), y = *(const f32x4*)(cw + j * FFN2 + FFN + c0 + 4 * h);
; #pragma unroll
;                 for (int e = 0; e < 4; ++e) { wa[j][4 * h + e] = x[e]; wg[j][4 * h + e] = y[e]; } }
; #pragma unroll
;         for (int h = 0; h < 2; ++h) { const f32x4 x = *(const f32x4*)(cb + c0 + 4 * h), y = *(const f32x4*)(cb + FFN + c0 + 4 * h);
; #pragma unroll
;             for (int e = 0; e < 4; ++e) { ba[4 * h + e] = x[e]; bg[4 * h + e] = y[e]; } }
;         const bf16_t* zp = Z + (size_t)r0 * FFN2 + c0; const u32x4 zero = (u32x4){0u, 0u, 0u, 0u};
;         u32x4 pa = zero, pg = zero; if (has_left) { pa = *(const u32x4*)(zp - FFN2); pg = *(const u32x4*)(zp - FFN2 + FFN); }
;         u32x4 ca = *(const u32x4*)(zp), cgv = *(const u32x4*)(zp + FFN);
.LBB0_1101:
	s_or_b64 exec, exec, s[2:3]
	v_mov_b32_e32 v1, v204
	v_readlane_b32 s2, v255, 17
	s_waitcnt lgkmcnt(0)
	s_barrier
	s_xor_b64 s[88:89], s[40:41], -1
	v_readlane_b32 s2, v254, 21
	v_readlane_b32 s3, v254, 22
	v_readlane_b32 s98, v255, 17
	s_load_dwordx2 s[38:39], s[2:3], 0x98
	s_load_dwordx2 s[40:41], s[2:3], 0xa0
	s_add_u32 s30, s54, 0x23a00000
	s_addc_u32 s31, s55, 0
	v_mov_b32_e32 v180, 0xbfb8aa3b
	v_mov_b32_e32 v181, 0xbfb8aa3b
	v_mov_b32_e32 v144, 1.0
	v_mov_b32_e32 v145, 1.0
	s_lshr_b32 s99, s98, 9
	v_lshrrev_b32_e32 v1, 6, v204
	v_lshl_add_u32 v1, v1, 8, s99
	v_and_b32_e32 v9, 63, v204
	v_lshl_or_b32 v1, v1, 6, v9
	s_mov_b32 s99, 0x2e8ba2e9
	v_mul_hi_u32 v2, v1, s99
	v_lshrrev_b32_e32 v2, 6, v2
	v_mul_u32_u24_e32 v3, 0x160, v2
	v_sub_u32_e32 v3, v1, v3
	v_lshlrev_b32_e32 v4, 5, v3
	v_mul_u32_u24_e32 v5, 180224, v2
	v_lshl_add_u32 v5, v3, 4, v5
	v_mul_u32_u24_e32 v6, 90112, v2
	v_lshl_add_u32 v6, v3, 4, v6
	s_lshr_b32 s99, s43, 4
	v_add_u32_e32 v7, s99, v2
	s_waitcnt lgkmcnt(0)
	s_sub_u32 s2, s64, 0x4000
	s_subb_u32 s3, s65, 0
	s_add_u32 s38, s38, 67584
	s_addc_u32 s39, s39, 0
	s_add_u32 s40, s40, 22528
	s_addc_u32 s41, s41, 0
	s_mov_b32 s98, 0
	s_mov_b32 s99, 0xffff0000
	global_load_dwordx4 v[152:155], v4, s[38:39]
	global_load_dwordx4 v[156:159], v4, s[38:39] offset:16
	v_add_u32_e32 v10, 11264, v4
	global_load_dwordx4 v[212:215], v10, s[38:39]
	global_load_dwordx4 v[216:219], v10, s[38:39] offset:16
	v_add_u32_e32 v11, 22528, v4
	global_load_dwordx4 v[160:163], v11, s[38:39]
	global_load_dwordx4 v[164:167], v11, s[38:39] offset:16
	v_add_u32_e32 v10, 33792, v4
	global_load_dwordx4 v[220:223], v10, s[38:39]
	global_load_dwordx4 v[224:227], v10, s[38:39] offset:16
	v_add_u32_e32 v11, 45056, v4
	global_load_dwordx4 v[168:171], v11, s[38:39]
	global_load_dwordx4 v[172:175], v11, s[38:39] offset:16
	v_add_u32_e32 v10, 56320, v4
	global_load_dwordx4 v[228:231], v10, s[38:39]
	global_load_dwordx4 v[232:235], v10, s[38:39] offset:16
	global_load_dwordx4 v[236:239], v4, s[40:41]
	global_load_dwordx4 v[240:243], v4, s[40:41] offset:16
	v_add_u32_e32 v11, 11264, v4
	global_load_dwordx4 v[244:247], v11, s[40:41]
	global_load_dwordx4 v[248:251], v11, s[40:41] offset:16
	v_add_u32_e32 v10, 7936, v5
	global_load_dwordx4 v[64:67], v10, s[2:3] offset:-2816 nt
	global_load_dwordx4 v[68:71], v10, s[2:3] offset:2816 nt
	global_load_dword v252, v4, s[40:41]
	v_add_u32_e32 v11, 19200, v5
	global_load_dwordx4 v[72:75], v11, s[2:3] offset:-2816 nt
	global_load_dwordx4 v[76:79], v11, s[2:3] offset:2816 nt
	global_load_dword v252, v4, s[40:41]
	v_add_u32_e32 v10, 30464, v5
	global_load_dwordx4 v[80:83], v10, s[2:3] offset:-2816 nt
	global_load_dwordx4 v[84:87], v10, s[2:3] offset:2816 nt
	global_load_dword v252, v4, s[40:41]
	v_add_u32_e32 v11, 41728, v5
	global_load_dwordx4 v[88:91], v11, s[2:3] offset:-2816 nt
	global_load_dwordx4 v[92:95], v11, s[2:3] offset:2816 nt
	global_load_dword v252, v4, s[40:41]
	v_add_u32_e32 v10, 52992, v5
	global_load_dwordx4 v[96:99], v10, s[2:3] offset:-2816 nt
	global_load_dwordx4 v[100:103], v10, s[2:3] offset:2816 nt
	global_load_dword v252, v4, s[40:41]
	v_add_u32_e32 v11, 64256, v5
	global_load_dwordx4 v[104:107], v11, s[2:3] offset:-2816 nt
	global_load_dwordx4 v[108:111], v11, s[2:3] offset:2816 nt
	global_load_dword v252, v4, s[40:41]
	v_add_u32_e32 v10, 75520, v5
	global_load_dwordx4 v[112:115], v10, s[2:3] offset:-2816 nt
	global_load_dwordx4 v[116:119], v10, s[2:3] offset:2816 nt
	global_load_dword v252, v4, s[40:41]
	v_add_u32_e32 v11, 86784, v5
	global_load_dwordx4 v[120:123], v11, s[2:3] offset:-2816 nt
	global_load_dwordx4 v[124:127], v11, s[2:3] offset:2816 nt
	global_load_dword v252, v4, s[40:41]
	v_add_u32_e32 v10, 98048, v5
	global_load_dwordx4 v[128:131], v10, s[2:3] offset:-2816 nt
	global_load_dwordx4 v[132:135], v10, s[2:3] offset:2816 nt
	global_load_dword v252, v4, s[40:41]
